# P2: half the workgroups (blockIdx bit3) run gla/attn_prompt items before the HBM-bound sample-attention+transpose stage, so the two halves overlap HBM-bound and compute-bound work
# baseline (speedup 1.0000x reference)
; #define LAS __attribute__((address_space(3)))
; __device__ __forceinline__ int fresh_tid() { int t = threadIdx.x; asm volatile("" : "+v"(t)); return t; }
; __device__ __forceinline__ void side_transposes(const P& p, LAS unsigned char* lds, int sw, int lane, int G) {
;     unsigned char* ws = p.ws;
;     LAS float* scr = (LAS float*)(lds + sw * 16640);
;     bf16_t* BTO = (bf16_t*)(ws + O_BTO); bf16_t* BTU = (bf16_t*)(ws + O_BTU); bf16_t* BTD = (bf16_t*)(ws + O_BTD);
;     constexpr int I_O = 32 * 32, I_U = 32 * 128, I_D = 128 * 32;
;     for (int it = sw * G + blockIdx.x; it < I_O + I_U + I_D; it += 4 * G) {
;         int r = it;
;         if (r < I_O) { const int kb = r / 32, nb = r % 32; tr_item(p.w_out, DM, kb * 64, nb * 64, 64, nullptr, BTO, DM, nb * 64, scr, lane); continue; }
;         r -= I_O;
;         if (r < I_U) { const int kb = r / 128, nb = r % 128; tr_item(p.w_up, DFF, kb * 64, nb * 64, 64, p.ffn_norm_w, BTU, DM, nb * 64, scr, lane); continue; }
;         r -= I_U;
;         { const int kb = r / 32, nb = r % 32; tr_item(p.w_down, DM, kb * 64, nb * 64, 64, nullptr, BTD, DFF, nb * 64, scr, lane); }
; __global__ void __launch_bounds__(NTHR) fwd_megakernel(P p) {
;     ...
;         { const int t0 = fresh_tid(); const int w = __builtin_amdgcn_readfirstlane(t0 >> 6);
;           __syncthreads();
;           if (w < 4) { for (int wi = w * G + blockIdx.x; wi < 1024; wi += G * 4) attn_sample_item(p, wi, t0 & 63); }
;           else side_transposes(p, lds, w - 4, t0 & 63, G); }
.LBB0_376:
	s_or_b64 exec, exec, s[0:1]
	v_mov_b32_e32 v42, v230
	s_waitcnt lgkmcnt(0)
	s_barrier
	s_mov_b32 s98, 0
	s_bitcmp1_b32 s2, 3
	s_cbranch_scc0 .Lp2_hstage
	v_writelane_b32 v255, s8, 24
	v_writelane_b32 v255, s9, 25
	v_writelane_b32 v255, s10, 26
	v_writelane_b32 v255, s11, 27
	v_writelane_b32 v255, s42, 28
	v_writelane_b32 v255, s43, 29
	v_writelane_b32 v255, s44, 30
	v_writelane_b32 v255, s45, 31
	v_writelane_b32 v255, s46, 32
	v_writelane_b32 v255, s47, 33
	v_writelane_b32 v255, s48, 34
	v_writelane_b32 v255, s49, 35
	v_writelane_b32 v255, s56, 36
	v_writelane_b32 v255, s57, 37
	v_writelane_b32 v255, s58, 38
	v_writelane_b32 v255, s59, 39
	s_mov_b32 s98, 1
	s_branch .LBB0_479
.Lp2_hstage:
	s_nop 0
	v_readfirstlane_b32 s0, v42
	s_ashr_i32 s3, s0, 6
	s_cmp_gt_i32 s3, 3
	s_mov_b64 s[0:1], -1
	s_barrier
	s_cbranch_scc0 .LBB0_453
	s_add_i32 s0, s3, -4
	s_mul_i32 s1, s0, s34
	s_add_i32 s16, s1, s2
	v_writelane_b32 v255, s3, 21
	s_cmpk_gt_i32 s16, 0x23ff
	s_cbranch_scc1 .LBB0_452
	v_lshlrev_b32_e32 v0, 3, v42
	v_and_b32_e32 v0, 56, v0
	s_mulk_i32 s0, 0x4100
	v_mov_b32_e32 v1, 0
	v_mul_u32_u24_e32 v4, 0x104, v0
	v_lshlrev_b32_e32 v0, 1, v0
	s_add_i32 s3, s0, 0
	v_bfe_u32 v44, v42, 3, 3
	v_lshl_add_u64 v[6:7], s[70:71], 0, v[0:1]
	s_mov_b64 s[0:1], 0x6126400
	v_and_b32_e32 v8, 63, v42
	v_lshl_add_u64 v[2:3], v[6:7], 0, s[0:1]
	v_lshlrev_b32_e32 v0, 2, v44
	s_mov_b64 s[0:1], 0x4126400
	s_lshl_b32 s17, s34, 2
	v_lshl_add_u32 v43, v8, 2, s3
	v_add3_u32 v45, s3, v4, v0
	v_lshl_add_u64 v[4:5], v[6:7], 0, s[0:1]
	s_mov_b64 s[0:1], 0x3926400
	s_cmp_lg_u64 s[44:45], 0
	v_or_b32_e32 v46, 8, v44
	v_or_b32_e32 v47, 16, v44
	v_or_b32_e32 v48, 24, v44
	v_or_b32_e32 v49, 32, v44
	v_or_b32_e32 v50, 40, v44
	v_or_b32_e32 v51, 48, v44
	v_or_b32_e32 v52, 56, v44
	v_lshl_add_u64 v[6:7], v[6:7], 0, s[0:1]
	s_cselect_b64 s[4:5], -1, 0
	s_lshl_b32 s18, s16, 6
	s_lshl_b32 s19, s34, 8
	s_lshl_b32 s20, s16, 1
	s_movk_i32 s93, 0x2000
	s_mov_b32 s28, 0x8000
	s_mov_b32 s52, 0x10000
	s_mov_b32 s64, 0x18000
	s_mov_b32 s79, 0x20000
	s_mov_b32 s83, 0x28000
	s_mov_b32 s87, 0x30000
	s_mov_b32 s91, 0x38000
	s_mov_b32 s94, 0x3e000
	s_mov_b32 s95, 0x40000
	s_mov_b32 s96, 0x42000
	s_mov_b32 s97, 0x44000
	s_mov_b32 s23, 0x46000
	s_mov_b32 s26, 0x48000
	s_mov_b32 s27, 0x4a000
	s_mov_b32 s33, 0x4c000
	s_mov_b32 s76, 0x4e000
	s_mov_b32 s77, 0x50000
	s_mov_b32 s3, 0x52000
	s_mov_b32 s21, 0x54000
	s_mov_b32 s24, 0x56000
	s_mov_b32 s25, 0x58000
	s_mov_b32 s29, 0x5a000
	s_mov_b32 s30, 0x5c000
	s_mov_b32 s31, 0x5e000
	s_mov_b32 s53, 0x60000
	s_mov_b32 s62, 0x62000
	s_mov_b32 s63, 0x64000
	s_mov_b32 s65, 0x66000
	s_mov_b32 s75, 0x68000
	s_mov_b32 s78, 0x6a000
	s_mov_b32 s80, 0x6c000
	s_mov_b32 s81, 0x6e000
	s_mov_b32 s82, 0x70000
	s_mov_b32 s84, 0x72000
	s_mov_b32 s85, 0x74000
	s_mov_b32 s86, 0x76000
	s_mov_b32 s88, 0x78000
	s_mov_b32 s89, 0x7a000
	s_mov_b32 s90, 0x7c000
	s_mov_b32 s92, 0x7e000
	v_lshlrev_b32_e32 v0, 2, v8
	v_add_u32_e32 v53, 0x400, v43
	v_add_u32_e32 v54, 0x800, v43
	v_add_u32_e32 v55, 0xc00, v43
	v_add_u32_e32 v56, 0x1000, v43
	v_add_u32_e32 v57, 0x1400, v43
	v_add_u32_e32 v58, 0x1800, v43
	v_add_u32_e32 v59, 0x1c00, v43
	v_add_u32_e32 v60, 0x2000, v43
	v_add_u32_e32 v61, 0x2400, v43
	v_add_u32_e32 v62, 0x2800, v43
	v_add_u32_e32 v63, 0x2c00, v43
	v_add_u32_e32 v64, 0x3000, v43
	v_add_u32_e32 v65, 0x3400, v43
	v_add_u32_e32 v66, 0x3800, v43
	v_add_u32_e32 v67, 0x3c00, v43
	v_add_u32_e32 v68, 0x400, v45
	s_mov_b32 s7, 0
	s_branch .LBB0_380

; #define LAS __attribute__((address_space(3)))
; __device__ __forceinline__ int fresh_tid() { int t = threadIdx.x; asm volatile("" : "+v"(t)); return t; }
; __device__ __forceinline__ float logsig(float x) { return fminf(x, 0.f) - __logf(1.f + __expf(-fabsf(x))); }
; __device__ __forceinline__ void gla_sample_item(const P& p, LAS unsigned char* lds, int it, int tid) {
;     unsigned char* ws = p.ws;
;     const int bs = it >> 3, h = (it >> 1) & 3, vh = it & 1;
;     LAS float* sA = (LAS float*)lds;
;     LAS float* sK = sA + 512;
;     LAS float* sQ = sK + 512;
;     LAS float* sRed = sQ + 512;
;     const float* ACC1 = (const float*)(ws + O_ACC1); const float* rstd1 = (const float*)(ws + O_RSTD1);
;     __syncthreads();
;     { const int i = tid >> 7, k = tid & 127; const int row = TP + bs * 4 + i;
;       const float* glr = (const float*)(ws + O_GLR) + (size_t)row * 16;
;       float x = p.b_gk[h * 128 + k];
; #pragma unroll
;       for (int r = 0; r < 16; ++r) x += glr[r] * p.w_gk_up[r * 512 + h * 128 + k];
;       sA[tid] = __expf(logsig(x) * (1.f / 16.f));
;       const float rs = rstd1[row];
;       sK[tid] = acc1_1(ACC1, bs * 4 + i, 512 + h * 128 + k) * rs;
;       sQ[tid] = acc1_1(ACC1, bs * 4 + i, h * 128 + k) * rs * 0.08838834764831845f; }
;     const int kq = tid >> 5, vc4 = tid & 31, v = vh * 128 + 4 * vc4;
;     const float* s0 = p.state_gla + (((size_t)bs * 4 + h) * 128 + kq * 8) * 256 + v;
; __global__ void __launch_bounds__(NTHR) fwd_megakernel(P p) {
;     ...
;         for (int rep = 0; rep < NREP(16); ++rep) { const int t0 = fresh_tid(); for (int it = blockIdx.x; it < 256; it += G) gla_sample_item(p, lds, it, t0); }
;         for (int rep = 0; rep < NREP(32); ++rep) { const int t0 = fresh_tid(); for (int it = blockIdx.x; it < 512; it += G) gla_a_item(p, lds, it, t0); }
.LBB0_479:
	s_cmp_eq_u32 s98, 2
	s_cbranch_scc1 .Lp2_finish
	s_cmpk_lt_i32 s2, 0x100
	s_cselect_b64 s[42:43], -1, 0
	v_mov_b32_e32 v0, v230
	s_and_b64 vcc, exec, s[42:43]
	s_cbranch_vccz .LBB0_482
	v_lshlrev_b32_e32 v1, 2, v0
	s_add_u32 s4, s70, 0x18426400
	v_ashrrev_i32_e32 v2, 5, v0
	v_and_b32_e32 v37, 0x7c, v1
	s_addc_u32 s5, s71, 0
	v_ashrrev_i32_e32 v21, 7, v0
	v_and_b32_e32 v20, 0x7f, v0
	v_add_u32_e32 v36, 0, v1
	v_lshlrev_b32_e32 v22, 3, v2
	v_lshlrev_b32_e32 v1, 9, v2
	v_lshlrev_b32_e32 v2, 2, v37
	v_and_b32_e32 v0, 0xffffffe0, v0
	s_add_u32 s6, s68, 0x6300000
	v_add3_u32 v38, 0, v1, v2
	v_add_u32_e32 v39, 0, v0
	v_lshlrev_b32_e32 v0, 13, v21
	v_lshlrev_b32_e32 v1, 2, v20
	v_mov_b32_e32 v25, 0
	s_addc_u32 s7, s69, 0
	s_mov_b32 s15, 0
	v_ashrrev_i32_e32 v23, 31, v22
	v_add3_u32 v40, 0, v0, v1
	s_lshl_b32 s3, s2, 7
	s_lshl_b32 s18, s34, 7
	s_movk_i32 s19, 0x2000
	s_movk_i32 s20, 0x1000
	s_movk_i32 s21, 0x3000
	s_movk_i32 s23, 0x4000
	s_movk_i32 s24, 0x5000
	s_movk_i32 s25, 0x6000
	s_movk_i32 s26, 0x7000
	s_mov_b32 s27, 0xbfb8aa3b
	s_mov_b32 s28, 0x800000
	s_mov_b32 s29, 0x3f317217
	s_mov_b32 s30, 0x7f800000
	v_mov_b32_e32 v41, 0x41b17218
	v_mov_b64_e32 v[26:27], s[8:9]
	s_mov_b32 s31, 0x300000
	s_mov_b32 s33, 0x600000
	s_mov_b32 s44, 0x900000
	s_mov_b32 s45, 0xc00000
	s_mov_b32 s46, 0xf00000
	s_mov_b32 s47, 0x1200000
	s_mov_b32 s48, 0x1500000
	s_mov_b64 s[16:17], 0x1000
	v_mov_b32_e32 v42, 0x6000
	v_lshlrev_b32_e32 v28, 2, v20
	v_mov_b32_e32 v29, v25
	s_mov_b32 s49, s2

; __device__ __forceinline__ int fresh_tid() { int t = threadIdx.x; asm volatile("" : "+v"(t)); return t; }
; #define GRID_SYNC() xcd_barrier(xbar)
; __global__ void __launch_bounds__(NTHR) fwd_megakernel(P p) {
;     ...
;         { const int t0 = fresh_tid(); const int w = __builtin_amdgcn_readfirstlane(t0 >> 6);
;           __syncthreads();
;           if (w < 4) { for (int wi = w * G + blockIdx.x; wi < 1024; wi += G * 4) attn_sample_item(p, wi, t0 & 63); }
;           else side_transposes(p, lds, w - 4, t0 & 63, G); }
;         for (int rep = 0; rep < NREP(16); ++rep) { const int t0 = fresh_tid(); for (int it = blockIdx.x; it < 256; it += G) gla_sample_item(p, lds, it, t0); }
;         for (int rep = 0; rep < NREP(32); ++rep) { const int t0 = fresh_tid(); for (int it = blockIdx.x; it < 512; it += G) gla_a_item(p, lds, it, t0); }
;         for (int rep = 0; rep < NREP(64); ++rep) attn_prompt_loop(p, lds, fresh_tid(), G);
;     }
;     GRID_SYNC();
.LBB0_530:
	v_readlane_b32 s74, v255, 1
	v_readlane_b32 s75, v255, 2
	s_cmp_eq_u32 s98, 1
	s_cbranch_scc0 .LBB0_531
	v_writelane_b32 v255, s0, 40
	v_writelane_b32 v255, s1, 41
	v_writelane_b32 v255, s16, 42
	v_writelane_b32 v255, s17, 43
	v_writelane_b32 v255, s21, 44
	v_writelane_b32 v255, s24, 45
	v_writelane_b32 v255, s25, 46
	v_writelane_b32 v255, s28, 47
	v_writelane_b32 v255, s29, 48
	v_writelane_b32 v255, s42, 49
	v_writelane_b32 v255, s43, 50
	v_writelane_b32 v255, s44, 51
	v_writelane_b32 v255, s45, 52
	v_writelane_b32 v255, s46, 53
	v_writelane_b32 v255, s47, 54
	v_writelane_b32 v255, s62, 55
	v_writelane_b32 v255, s74, 56
	v_writelane_b32 v255, s91, 57
	v_writelane_b32 v255, s94, 58
	v_writelane_b32 v255, s95, 59
	v_writelane_b32 v255, s96, 60
	v_writelane_b32 v255, s97, 61
	v_readlane_b32 s8, v255, 24
	v_readlane_b32 s9, v255, 25
	v_readlane_b32 s10, v255, 26
	v_readlane_b32 s11, v255, 27
	v_readlane_b32 s42, v255, 28
	v_readlane_b32 s43, v255, 29
	v_readlane_b32 s44, v255, 30
	v_readlane_b32 s45, v255, 31
	v_readlane_b32 s46, v255, 32
	v_readlane_b32 s47, v255, 33
	v_readlane_b32 s48, v255, 34
	v_readlane_b32 s49, v255, 35
	v_readlane_b32 s56, v255, 36
	v_readlane_b32 s57, v255, 37
	v_readlane_b32 s58, v255, 38
	v_readlane_b32 s59, v255, 39
	v_mov_b32_e32 v42, v230
	s_mov_b32 s98, 2
	s_waitcnt vmcnt(0) lgkmcnt(0)
	s_branch .Lp2_hstage
.Lp2_finish:
	v_readlane_b32 s0, v255, 40
	v_readlane_b32 s1, v255, 41
	v_readlane_b32 s16, v255, 42
	v_readlane_b32 s17, v255, 43
	v_readlane_b32 s21, v255, 44
	v_readlane_b32 s24, v255, 45
	v_readlane_b32 s25, v255, 46
	v_readlane_b32 s28, v255, 47
	v_readlane_b32 s29, v255, 48
	v_readlane_b32 s42, v255, 49
	v_readlane_b32 s43, v255, 50
	v_readlane_b32 s44, v255, 51
	v_readlane_b32 s45, v255, 52
	v_readlane_b32 s46, v255, 53
	v_readlane_b32 s47, v255, 54
	v_readlane_b32 s62, v255, 55
	v_readlane_b32 s74, v255, 56
	v_readlane_b32 s91, v255, 57
	v_readlane_b32 s94, v255, 58
	v_readlane_b32 s95, v255, 59
	v_readlane_b32 s96, v255, 60
	v_readlane_b32 s97, v255, 61

; #define LAS __attribute__((address_space(3)))
; __global__ void __launch_bounds__(NTHR) fwd_megakernel(P p) {
;     extern __shared__ __attribute__((aligned(16))) unsigned char smem[];
;     LAS unsigned char* lds = (LAS unsigned char*)smem;
;     cg::grid_group grid = cg::this_grid();
;     const int G = gridDim.x;
;     unsigned char* ws = p.ws;
;     if (threadIdx.x < 4) ((LAS unsigned*)(lds + LDS_BYTES - 16))[threadIdx.x] = 0u;
;     __syncthreads();
;     XcdBarrier xbar = xcd_barrier_post((unsigned*)(ws + O_BAR), (volatile LAS unsigned*)(lds + LDS_BYTES - 16));
;     if (p.ws == nullptr) grid.sync();
	.amdhsa_kernel _Z14fwd_megakernel1P
		.amdhsa_group_segment_fixed_size 0
		.amdhsa_private_segment_fixed_size 0
		.amdhsa_kernarg_size 400
		.amdhsa_user_sgpr_count 2
		.amdhsa_user_sgpr_dispatch_ptr 0
		.amdhsa_user_sgpr_queue_ptr 0
		.amdhsa_user_sgpr_kernarg_segment_ptr 1
		.amdhsa_user_sgpr_dispatch_id 0
		.amdhsa_user_sgpr_kernarg_preload_length 0
		.amdhsa_user_sgpr_kernarg_preload_offset 0
		.amdhsa_user_sgpr_private_segment_size 0
		.amdhsa_uses_dynamic_stack 0
		.amdhsa_enable_private_segment 0
		.amdhsa_system_sgpr_workgroup_id_x 1
		.amdhsa_system_sgpr_workgroup_id_y 0
		.amdhsa_system_sgpr_workgroup_id_z 0
		.amdhsa_system_sgpr_workgroup_info 0
		.amdhsa_system_vgpr_workitem_id 2
		.amdhsa_next_free_vgpr 256
		.amdhsa_next_free_sgpr 99
		.amdhsa_accum_offset 256
		.amdhsa_reserve_vcc 1
		.amdhsa_float_round_mode_32 0
		.amdhsa_float_round_mode_16_64 0
		.amdhsa_float_denorm_mode_32 3
		.amdhsa_float_denorm_mode_16_64 3
		.amdhsa_dx10_clamp 1
		.amdhsa_ieee_mode 1
		.amdhsa_fp16_overflow 0
		.amdhsa_tg_split 0
		.amdhsa_exception_fp_ieee_invalid_op 0
		.amdhsa_exception_fp_denorm_src 0
		.amdhsa_exception_fp_ieee_div_zero 0
		.amdhsa_exception_fp_ieee_overflow 0
		.amdhsa_exception_fp_ieee_underflow 0
		.amdhsa_exception_fp_ieee_inexact 0
		.amdhsa_exception_int_div_zero 0
	.end_amdhsa_kernel

; #define LAS __attribute__((address_space(3)))
; __global__ void __launch_bounds__(NTHR) fwd_megakernel(P p) {
;     extern __shared__ __attribute__((aligned(16))) unsigned char smem[];
;     LAS unsigned char* lds = (LAS unsigned char*)smem;
.Lfunc_end0:
	.size	_Z14fwd_megakernel1P, .Lfunc_end0-_Z14fwd_megakernel1P
	.set _Z14fwd_megakernel1P.num_vgpr, 256
	.set _Z14fwd_megakernel1P.num_agpr, 0
	.set _Z14fwd_megakernel1P.numbered_sgpr, 99
	.set _Z14fwd_megakernel1P.num_named_barrier, 0
	.set _Z14fwd_megakernel1P.private_seg_size, 0
	.set _Z14fwd_megakernel1P.uses_vcc, 1
	.set _Z14fwd_megakernel1P.uses_flat_scratch, 0
	.set _Z14fwd_megakernel1P.has_dyn_sized_stack, 0
	.set _Z14fwd_megakernel1P.has_recursion, 0
	.set _Z14fwd_megakernel1P.has_indirect_call, 0

; #define LAS __attribute__((address_space(3)))
; __global__ void __launch_bounds__(NTHR) fwd_megakernel(P p) {
;     extern __shared__ __attribute__((aligned(16))) unsigned char smem[];
;     LAS unsigned char* lds = (LAS unsigned char*)smem;
amdhsa.kernels:
  - .agpr_count:     0
    .args:
      - .offset:         0
        .size:           144
        .value_kind:     by_value
      - .offset:         144
        .size:           4
        .value_kind:     hidden_block_count_x
      - .offset:         148
        .size:           4
        .value_kind:     hidden_block_count_y
      - .offset:         152
        .size:           4
        .value_kind:     hidden_block_count_z
      - .offset:         156
        .size:           2
        .value_kind:     hidden_group_size_x
      - .offset:         158
        .size:           2
        .value_kind:     hidden_group_size_y
      - .offset:         160
        .size:           2
        .value_kind:     hidden_group_size_z
      - .offset:         162
        .size:           2
        .value_kind:     hidden_remainder_x
      - .offset:         164
        .size:           2
        .value_kind:     hidden_remainder_y
      - .offset:         166
        .size:           2
        .value_kind:     hidden_remainder_z
      - .offset:         184
        .size:           8
        .value_kind:     hidden_global_offset_x
      - .offset:         192
        .size:           8
        .value_kind:     hidden_global_offset_y
      - .offset:         200
        .size:           8
        .value_kind:     hidden_global_offset_z
      - .offset:         208
        .size:           2
        .value_kind:     hidden_grid_dims
      - .offset:         232
        .size:           8
        .value_kind:     hidden_multigrid_sync_arg
      - .offset:         264
        .size:           4
        .value_kind:     hidden_dynamic_lds_size
    .group_segment_fixed_size: 0
    .kernarg_segment_align: 8
    .kernarg_segment_size: 400
    .language:       OpenCL C
    .language_version:
      - 2
      - 0
    .max_flat_workgroup_size: 512
    .name:           _Z14fwd_megakernel1P
    .private_segment_fixed_size: 0
    .sgpr_count:     105
    .sgpr_spill_count: 25
    .symbol:         _Z14fwd_megakernel1P.kd
    .uniform_work_group_size: 1
    .uses_dynamic_stack: false
    .vgpr_count:     256
    .vgpr_spill_count: 0
    .wavefront_size: 64
